# hg_b phase B: o_inter read-modify-write with 8-byte accesses after transposing the result tile through a private LDS scratch
# baseline (speedup 1.0000x reference)
; #define LAS __attribute__((address_space(3)))
; __device__ __forceinline__ void hg_b_item(const Params& p, LAS unsigned char* lds, int item, bool dry = false) {
;     ...
;     LAS bf16_t* SB = (LAS bf16_t*)lds;
;     const int b = item >> 6, h = (item >> 3) & 7, es = item & 7;
;     const int fr = lane & 15, fq = lane >> 4;
;     const bf16_t* Z = (const bf16_t*)(WSP + WS_Z); bf16_t* OI = (bf16_t*)(WSP + WS_OI); const float* DEC = (const float*)(WSP + WS_DEC);
;     f32x4 S = (f32x4){0.f, 0.f, 0.f, 0.f};
;     const int eg = 16 * es + fr, dg = 16 * wave + fr;
;     const bf16_t* pV = Z + (size_t)(b * SEQ + (eg >> 1)) * ZW + 4096 + h * 128 + (eg & 1) * 64 + 8 * fq;
;     const bf16_t* pK = Z + (size_t)(b * SEQ + (dg >> 1)) * ZW + 3072 + h * 128 + (dg & 1) * 64 + 8 * fq;
;     const bf16_t* pQ = Z + (size_t)(b * SEQ + fr) * ZW + 2048 + h * 128 + 8 * fq;
;     bf16_t* pO = OI + (size_t)(b * SEQ + 4 * fq) * D + h * 128 + 16 * es + fr;
;     const float* pD = DEC + (size_t)((b * 8 + h) * 64) * 128 + dg;
;     __syncthreads();
.LBB0_202:
	s_lshl_b32 s4, s50, 3
	s_and_b32 s4, s4, 56
	s_and_b32 s5, s50, 0xffffffc0
	s_or_b32 s4, s4, s5
	s_bfe_u32 s5, s50, 0x30003
	s_or_b32 s8, s4, s5
	s_and_b64 s[4:5], s[6:7], exec
	v_readfirstlane_b32 s24, v34
	v_readfirstlane_b32 s25, v35
	v_mov_b32_e32 v3, v162
	s_cselect_b32 s4, s8, s50
	v_readfirstlane_b32 s5, v3
	s_ashr_i32 s51, s5, 6
	v_and_b32_e32 v8, 15, v3
	s_ashr_i32 s16, s4, 6
	v_lshl_or_b32 v2, s51, 4, v8
	s_lshl_b32 s55, s16, 12
	v_ashrrev_i32_e32 v0, 1, v2
	s_bfe_u32 s17, s4, 0x30003
	s_lshl_b32 s4, s4, 4
	v_add_u32_e32 v0, s55, v0
	s_and_b32 s54, s4, 0x70
	v_mad_i64_i32 v[22:23], s[4:5], v0, s3, 0
	v_or_b32_e32 v0, s55, v8
	v_mov_b64_e32 v[4:5], s[24:25]
	v_bfe_u32 v9, v3, 4, 2
	v_mad_i64_i32 v[4:5], s[4:5], v0, s3, v[4:5]
	s_lshl_b32 s8, s17, 8
	v_lshl_add_u64 v[4:5], v[4:5], 0, s[8:9]
	v_lshlrev_b32_e32 v0, 4, v9
	v_lshl_add_u64 v[4:5], v[4:5], 0, v[0:1]
	v_lshl_add_u64 v[24:25], v[4:5], 0, s[10:11]
	v_lshl_or_b32 v4, v9, 2, s55
	v_ashrrev_i32_e32 v5, 31, v4
	v_lshlrev_b64 v[4:5], 11, v[4:5]
	v_lshl_add_u64 v[4:5], s[24:25], 0, v[4:5]
	v_lshl_add_u64 v[4:5], v[4:5], 0, s[8:9]
	s_lshl_b32 s4, s54, 1
	s_mov_b32 s5, s9
	v_lshl_add_u64 v[4:5], v[4:5], 0, s[4:5]
	v_lshlrev_b32_e32 v6, 1, v8
	v_mov_b32_e32 v7, v1
	v_lshl_add_u64 v[4:5], v[4:5], 0, v[6:7]
	v_lshl_add_u64 v[26:27], v[4:5], 0, s[12:13]
	v_or_b32_e32 v5, s54, v8
	v_lshrrev_b16_e32 v5, 1, v5
	v_or_b32_e32 v5, s55, v5
	v_mad_i64_i32 v[28:29], s[4:5], v5, s3, 0
	v_lshlrev_b32_e32 v3, 7, v3
	v_or_b32_e32 v5, s8, v28
	v_and_b32_e32 v3, 0x80, v3
	s_lshl_b32 s16, s16, 9
	s_lshl_b32 s17, s17, 6
	v_mul_u32_u24_e32 v4, 0x110, v8
	v_or3_b32 v28, v5, v3, v0
	v_or_b32_e32 v5, s8, v22
	s_lshl_b32 s4, s51, 5
	v_add3_u32 v4, 0, v0, v4
	v_or3_b32 v22, v5, v3, v0
	v_mov_b32_e32 v0, s4
	s_or_b32 s4, s16, s17
	s_ashr_i32 s5, s4, 31
	v_mad_u32_u24 v0, v9, s26, v0
	s_lshl_b64 s[4:5], s[4:5], 9
	v_ashrrev_i32_e32 v3, 31, v2
	s_mul_i32 s56, s51, 0x1100
	v_or_b32_e32 v0, v0, v6
	v_lshl_add_u64 v[30:31], v[2:3], 2, s[4:5]
	v_mov_b32_e32 v2, v1
	v_mov_b32_e32 v3, v1
	v_add_u32_e32 v37, 0, v0
	v_mov_b32_e32 v0, v1
	v_add_u32_e32 v38, s56, v4
	v_mov_b64_e32 v[4:5], v[2:3]
	v_mov_b64_e32 v[2:3], v[0:1]
	v_lshrrev_b32_e32 v174, 4, v162
	v_and_b32_e32 v174, 7, v174
	v_and_b32_e32 v175, 15, v162
	s_lshr_b32 s98, s54, 1
	s_add_i32 s98, s98, s55
	v_add_u32_e32 v176, s98, v174
	v_mul_u32_u24_e32 v176, 0x3000, v176
	v_lshl_add_u32 v176, v175, 4, v176
	v_add_u32_e32 v176, s8, v176
	v_lshrrev_b32_e32 v177, 7, v162
	v_mul_u32_u24_e32 v170, 0xc0000, v177
	v_add_u32_e32 v170, v170, v176
	v_add_u32_e32 v170, 0x402000, v170
	global_load_dwordx4 v[80:83], v170, s[24:25]
	v_add_u32_e32 v96, 0x300000, v170
	global_load_dwordx4 v[84:87], v96, s[24:25]
	v_add_u32_e32 v97, 0x600000, v170
	global_load_dwordx4 v[88:91], v97, s[24:25]
	v_add_u32_e32 v98, 0x900000, v170
	global_load_dwordx4 v[92:95], v98, s[24:25]
	v_add_u32_e32 v170, 0xc00000, v170
	v_mul_u32_u24_e32 v171, 0x1100, v177
	v_lshrrev_b32_e32 v177, 3, v175
	v_lshl_add_u32 v177, v174, 1, v177
	v_mul_u32_u24_e32 v177, 0x90, v177
	v_and_b32_e32 v174, 7, v175
	v_lshl_add_u32 v177, v174, 4, v177
	v_add_u32_e32 v171, v171, v177
	v_add_u32_e32 v171, 0x12000, v171
	v_and_b32_e32 v174, 15, v162
	v_bfe_u32 v175, v162, 4, 2
	v_mul_u32_u24_e32 v172, 0x90, v174
	v_lshl_add_u32 v172, v175, 4, v172
	v_add_u32_e32 v172, 0x12000, v172
	s_waitcnt vmcnt(0)
	ds_write_b128 v171, v[80:83]
	ds_write_b128 v171, v[84:87] offset:17408
	ds_write_b128 v171, v[88:91] offset:34816
	ds_write_b128 v171, v[92:95] offset:52224
	s_waitcnt lgkmcnt(0)
	s_mul_i32 s99, s55, 0x3000
	s_add_i32 s99, s99, s8
	s_add_i32 s99, s99, 0x401000
	v_and_b32_e32 v174, 15, v162
	v_bfe_u32 v175, v162, 4, 2
	v_xor_b32_e32 v176, v174, v175
	v_lshlrev_b32_e32 v176, 4, v176
	v_mul_u32_u24_e32 v177, 0x3000, v175
	v_add_u32_e32 v178, v177, v176
	v_xor_b32_e32 v179, 64, v176
	v_add_u32_e32 v179, v179, v177
	v_add_u32_e32 v179, 0xc000, v179
	v_xor_b32_e32 v180, 128, v176
	v_add_u32_e32 v180, v180, v177
	v_add_u32_e32 v180, 0x18000, v180
	v_xor_b32_e32 v181, 192, v176
	v_add_u32_e32 v181, v181, v177
	v_add_u32_e32 v181, 0x24000, v181
	s_lshl_b32 s98, s51, 13
	s_add_i32 s98, s98, 0x12000
	v_lshlrev_b32_e32 v177, 8, v174
	v_add_u32_e32 v177, s98, v177
	v_add_u32_e32 v182, v177, v176
	v_xor_b32_e32 v183, 64, v176
	v_add_u32_e32 v183, v183, v177
	v_xor_b32_e32 v184, 128, v176
	v_add_u32_e32 v184, v184, v177
	v_xor_b32_e32 v185, 192, v176
	v_add_u32_e32 v185, v185, v177
	v_and_b32_e32 v176, 63, v162
	v_lshrrev_b32_e32 v177, 2, v176
	v_and_b32_e32 v176, 3, v176
	v_lshlrev_b32_e32 v186, 11, v177
	v_lshl_add_u32 v186, v176, 3, v186
	s_mul_i32 s98, s51, 0x1100
	v_mul_u32_u24_e32 v188, 0x50, v177
	v_lshl_add_u32 v188, v176, 4, v188
	v_add_u32_e32 v188, s98, v188
	v_mul_u32_u24_e32 v187, 0x140, v175
	v_lshl_add_u32 v187, v174, 2, v187
	v_add_u32_e32 v187, s98, v187
	s_mov_b32 s8, 0
	s_barrier

; __device__ __forceinline__ unsigned f2bf(float f) { unsigned u = __float_as_uint(f); return (u + 0x7fffu + ((u >> 16) & 1u)) >> 16; }
; __device__ __forceinline__ float bf2f(unsigned h) { return __uint_as_float(h << 16); }
; #define MFMA16(a, b, c) __builtin_amdgcn_mfma_f32_16x16x32_bf16((a), (b), (c), 0, 0, 0)
; __device__ __forceinline__ void hg_b_item(const Params& p, LAS unsigned char* lds, int item, bool dry = false) {
;     ...
;             for (int lt = 0; lt < 4; ++lt) { f32x4 acc = (f32x4){0.f, 0.f, 0.f, 0.f}; unsigned short oO[4];
; #pragma unroll
;                 for (int r = 0; r < 4; ++r) oO[r] = pO[(size_t)(nB * 64 + 16 * lt + r) * D];
; #pragma unroll
;                 for (int k = 0; k < 4; ++k) { const bf16x8 a = *(const bf16x8*)(pQ + roB + (size_t)(16 * lt) * ZW + 32 * k); acc = MFMA16(a, bS[k], acc); }
; #pragma unroll
;                 for (int r = 0; r < 4; ++r) { const float nv = bf2f(oO[r]) + acc[r]; if (!dry) pO[(size_t)(nB * 64 + 16 * lt + r) * D] = (bf16_t)f2bf(nv); else if (nv == 123456.0f) pO[0] = 0; } } }
.Lhgb_nostage:
	s_lshl_b32 s4, s8, 4
	s_add_i32 s4, s4, s51
	s_mul_i32 s5, s4, 0xc0000
	s_add_i32 s5, s5, s99
	s_add_u32 s54, s24, s5
	s_addc_u32 s55, s25, 0
	s_lshl_b32 s56, s4, 17
	v_readfirstlane_b32 s4, v26
	v_readfirstlane_b32 s5, v27
	s_add_u32 s4, s4, s56
	s_addc_u32 s5, s5, 0
	s_mov_b32 s59, 0xffff0000
	s_add_i32 s8, s8, 1
	v_lshl_add_u64 v[28:29], v[28:29], 0, s[20:21]
	v_lshl_add_u64 v[22:23], v[22:23], 0, s[20:21]
	v_lshl_add_u64 v[30:31], v[30:31], 0, s[22:23]
	s_lshl_b32 s58, s51, 13
	s_add_i32 s58, s58, 0x12000
	s_mov_b32 s60, s54
	s_mov_b32 s61, s55
	s_add_i32 m0, s58, 0x0
	s_nop 0
	global_load_lds_dwordx4 v178, s[60:61]
	s_add_i32 m0, s58, 0x400
	s_nop 0
	global_load_lds_dwordx4 v179, s[60:61]
	s_add_i32 m0, s58, 0x800
	s_nop 0
	global_load_lds_dwordx4 v180, s[60:61]
	s_add_i32 m0, s58, 0xc00
	s_nop 0
	global_load_lds_dwordx4 v181, s[60:61]
	s_mov_b32 s16, s4
	s_mov_b32 s17, s5
	global_load_dwordx2 v[100:101], v186, s[16:17]
	s_add_u32 s60, s54, 0x30000
	s_addc_u32 s61, s55, 0
	s_add_i32 m0, s58, 0x1000
	s_nop 0
	global_load_lds_dwordx4 v178, s[60:61]
	s_add_i32 m0, s58, 0x1400
	s_nop 0
	global_load_lds_dwordx4 v179, s[60:61]
	s_add_i32 m0, s58, 0x1800
	s_nop 0
	global_load_lds_dwordx4 v180, s[60:61]
	s_add_i32 m0, s58, 0x1c00
	s_nop 0
	global_load_lds_dwordx4 v181, s[60:61]
	s_add_u32 s16, s4, 0x8000
	s_addc_u32 s17, s5, 0
	global_load_dwordx2 v[102:103], v186, s[16:17]
	ds_read_b128 v[40:43], v38
	ds_read_b128 v[44:47], v38 offset:64
	ds_read_b128 v[48:51], v38 offset:128
	ds_read_b128 v[52:55], v38 offset:192
	s_waitcnt vmcnt(5)
	ds_read_b128 v[56:59], v182
	ds_read_b128 v[60:63], v183
	ds_read_b128 v[64:67], v184
	ds_read_b128 v[68:71], v185
	s_waitcnt lgkmcnt(0)
	v_mfma_f32_16x16x32_bf16 v[72:75], v[56:59], v[40:43], 0
	v_mfma_f32_16x16x32_bf16 v[72:75], v[60:63], v[44:47], v[72:75]
	v_mfma_f32_16x16x32_bf16 v[72:75], v[64:67], v[48:51], v[72:75]
	v_mfma_f32_16x16x32_bf16 v[72:75], v[68:71], v[52:55], v[72:75]
	v_lshlrev_b32_e32 v104, 16, v100
	v_and_b32_e32 v105, s59, v100
	v_lshlrev_b32_e32 v106, 16, v101
	v_and_b32_e32 v107, s59, v101
	s_nop 7
	s_nop 3
	ds_write_b32 v187, v72
	ds_write_b32 v187, v73 offset:80
	ds_write_b32 v187, v74 offset:160
	ds_write_b32 v187, v75 offset:240
	ds_read_b128 v[76:79], v188
	s_waitcnt lgkmcnt(0)
	v_add_f32_e32 v108, v76, v104
	v_add_f32_e32 v109, v77, v105
	v_add_f32_e32 v110, v78, v106
	v_add_f32_e32 v111, v79, v107
	v_bfe_u32 v112, v108, 16, 1
	v_bfe_u32 v113, v109, 16, 1
	v_bfe_u32 v114, v110, 16, 1
	v_bfe_u32 v115, v111, 16, 1
	v_add3_u32 v108, v108, v112, s27
	v_add3_u32 v109, v109, v113, s27
	v_add3_u32 v110, v110, v114, s27
	v_add3_u32 v111, v111, v115, s27
	v_lshrrev_b32_e32 v116, 16, v108
	v_lshrrev_b32_e32 v117, 16, v110
	v_and_or_b32 v118, v109, s59, v116
	v_and_or_b32 v119, v111, s59, v117
	s_mov_b32 s48, s4
	s_mov_b32 s49, s5
	global_store_dwordx2 v186, v[118:119], s[48:49]
	s_add_u32 s60, s54, 0x60000
	s_addc_u32 s61, s55, 0
	s_add_i32 m0, s58, 0x0
	s_nop 0
	global_load_lds_dwordx4 v178, s[60:61]
	s_add_i32 m0, s58, 0x400
	s_nop 0
	global_load_lds_dwordx4 v179, s[60:61]
	s_add_i32 m0, s58, 0x800
	s_nop 0
	global_load_lds_dwordx4 v180, s[60:61]
	s_add_i32 m0, s58, 0xc00
	s_nop 0
	global_load_lds_dwordx4 v181, s[60:61]
	s_add_u32 s16, s4, 0x10000
	s_addc_u32 s17, s5, 0
	global_load_dwordx2 v[100:101], v186, s[16:17]
	s_waitcnt vmcnt(6)
	ds_read_b128 v[56:59], v182 offset:4096
	ds_read_b128 v[60:63], v183 offset:4096
	ds_read_b128 v[64:67], v184 offset:4096
	ds_read_b128 v[68:71], v185 offset:4096
	s_waitcnt lgkmcnt(0)
	v_mfma_f32_16x16x32_bf16 v[72:75], v[56:59], v[40:43], 0
	v_mfma_f32_16x16x32_bf16 v[72:75], v[60:63], v[44:47], v[72:75]
	v_mfma_f32_16x16x32_bf16 v[72:75], v[64:67], v[48:51], v[72:75]
	v_mfma_f32_16x16x32_bf16 v[72:75], v[68:71], v[52:55], v[72:75]
	v_lshlrev_b32_e32 v104, 16, v102
	v_and_b32_e32 v105, s59, v102
	v_lshlrev_b32_e32 v106, 16, v103
	v_and_b32_e32 v107, s59, v103
	s_nop 7
	s_nop 3
	ds_write_b32 v187, v72
	ds_write_b32 v187, v73 offset:80
	ds_write_b32 v187, v74 offset:160
	ds_write_b32 v187, v75 offset:240
	ds_read_b128 v[76:79], v188
	s_waitcnt lgkmcnt(0)
	v_add_f32_e32 v108, v76, v104
	v_add_f32_e32 v109, v77, v105
	v_add_f32_e32 v110, v78, v106
	v_add_f32_e32 v111, v79, v107
	v_bfe_u32 v112, v108, 16, 1
	v_bfe_u32 v113, v109, 16, 1
	v_bfe_u32 v114, v110, 16, 1
	v_bfe_u32 v115, v111, 16, 1
	v_add3_u32 v108, v108, v112, s27
	v_add3_u32 v109, v109, v113, s27
	v_add3_u32 v110, v110, v114, s27
	v_add3_u32 v111, v111, v115, s27
	v_lshrrev_b32_e32 v116, 16, v108
	v_lshrrev_b32_e32 v117, 16, v110
	v_and_or_b32 v118, v109, s59, v116
	v_and_or_b32 v119, v111, s59, v117
	s_add_u32 s48, s4, 0x8000
	s_addc_u32 s49, s5, 0
	global_store_dwordx2 v186, v[118:119], s[48:49]
	s_add_u32 s60, s54, 0x90000
	s_addc_u32 s61, s55, 0
	s_add_i32 m0, s58, 0x1000
	s_nop 0
	global_load_lds_dwordx4 v178, s[60:61]
	s_add_i32 m0, s58, 0x1400
	s_nop 0
	global_load_lds_dwordx4 v179, s[60:61]
	s_add_i32 m0, s58, 0x1800
	s_nop 0
	global_load_lds_dwordx4 v180, s[60:61]
	s_add_i32 m0, s58, 0x1c00
	s_nop 0
	global_load_lds_dwordx4 v181, s[60:61]
	s_add_u32 s16, s4, 0x18000
	s_addc_u32 s17, s5, 0
	global_load_dwordx2 v[102:103], v186, s[16:17]
	s_waitcnt vmcnt(6)
	ds_read_b128 v[56:59], v182
	ds_read_b128 v[60:63], v183
	ds_read_b128 v[64:67], v184
	ds_read_b128 v[68:71], v185
	s_waitcnt lgkmcnt(0)
; __device__ __forceinline__ unsigned f2bf(float f) { unsigned u = __float_as_uint(f); return (u + 0x7fffu + ((u >> 16) & 1u)) >> 16; }
; __device__ __forceinline__ float bf2f(unsigned h) { return __uint_as_float(h << 16); }
; #define MFMA16(a, b, c) __builtin_amdgcn_mfma_f32_16x16x32_bf16((a), (b), (c), 0, 0, 0)
; __device__ __forceinline__ void hg_b_item(const Params& p, LAS unsigned char* lds, int item, bool dry = false) {
;     ...
;             for (int lt = 0; lt < 4; ++lt) { f32x4 acc = (f32x4){0.f, 0.f, 0.f, 0.f}; unsigned short oO[4];
; #pragma unroll
;                 for (int r = 0; r < 4; ++r) oO[r] = pO[(size_t)(nB * 64 + 16 * lt + r) * D];
; #pragma unroll
;                 for (int k = 0; k < 4; ++k) { const bf16x8 a = *(const bf16x8*)(pQ + roB + (size_t)(16 * lt) * ZW + 32 * k); acc = MFMA16(a, bS[k], acc); }
; #pragma unroll
;                 for (int r = 0; r < 4; ++r) { const float nv = bf2f(oO[r]) + acc[r]; if (!dry) pO[(size_t)(nB * 64 + 16 * lt + r) * D] = (bf16_t)f2bf(nv); else if (nv == 123456.0f) pO[0] = 0; } } }
	v_mfma_f32_16x16x32_bf16 v[72:75], v[56:59], v[40:43], 0
	v_mfma_f32_16x16x32_bf16 v[72:75], v[60:63], v[44:47], v[72:75]
	v_mfma_f32_16x16x32_bf16 v[72:75], v[64:67], v[48:51], v[72:75]
	v_mfma_f32_16x16x32_bf16 v[72:75], v[68:71], v[52:55], v[72:75]
	v_lshlrev_b32_e32 v104, 16, v100
	v_and_b32_e32 v105, s59, v100
	v_lshlrev_b32_e32 v106, 16, v101
	v_and_b32_e32 v107, s59, v101
	s_nop 7
	s_nop 3
	ds_write_b32 v187, v72
	ds_write_b32 v187, v73 offset:80
	ds_write_b32 v187, v74 offset:160
	ds_write_b32 v187, v75 offset:240
	ds_read_b128 v[76:79], v188
	s_waitcnt lgkmcnt(0)
	v_add_f32_e32 v108, v76, v104
	v_add_f32_e32 v109, v77, v105
	v_add_f32_e32 v110, v78, v106
	v_add_f32_e32 v111, v79, v107
	v_bfe_u32 v112, v108, 16, 1
	v_bfe_u32 v113, v109, 16, 1
	v_bfe_u32 v114, v110, 16, 1
	v_bfe_u32 v115, v111, 16, 1
	v_add3_u32 v108, v108, v112, s27
	v_add3_u32 v109, v109, v113, s27
	v_add3_u32 v110, v110, v114, s27
	v_add3_u32 v111, v111, v115, s27
	v_lshrrev_b32_e32 v116, 16, v108
	v_lshrrev_b32_e32 v117, 16, v110
	v_and_or_b32 v118, v109, s59, v116
	v_and_or_b32 v119, v111, s59, v117
	s_add_u32 s48, s4, 0x10000
	s_addc_u32 s49, s5, 0
	global_store_dwordx2 v186, v[118:119], s[48:49]
	s_add_u32 s60, s54, 0x600000
	s_addc_u32 s61, s55, 0
	s_add_i32 m0, s58, 0x0
	s_nop 0
	global_load_lds_dwordx4 v178, s[60:61]
	s_add_i32 m0, s58, 0x400
	s_nop 0
	global_load_lds_dwordx4 v179, s[60:61]
	s_add_i32 m0, s58, 0x800
	s_nop 0
	global_load_lds_dwordx4 v180, s[60:61]
	s_add_i32 m0, s58, 0xc00
	s_nop 0
	global_load_lds_dwordx4 v181, s[60:61]
	s_add_u32 s16, s4, 0x100000
	s_addc_u32 s17, s5, 0
	global_load_dwordx2 v[100:101], v186, s[16:17]
	s_waitcnt vmcnt(6)
	ds_read_b128 v[56:59], v182 offset:4096
	ds_read_b128 v[60:63], v183 offset:4096
	ds_read_b128 v[64:67], v184 offset:4096
	ds_read_b128 v[68:71], v185 offset:4096
	s_waitcnt lgkmcnt(0)
	v_mfma_f32_16x16x32_bf16 v[72:75], v[56:59], v[40:43], 0
	v_mfma_f32_16x16x32_bf16 v[72:75], v[60:63], v[44:47], v[72:75]
	v_mfma_f32_16x16x32_bf16 v[72:75], v[64:67], v[48:51], v[72:75]
	v_mfma_f32_16x16x32_bf16 v[72:75], v[68:71], v[52:55], v[72:75]
	v_lshlrev_b32_e32 v104, 16, v102
	v_and_b32_e32 v105, s59, v102
	v_lshlrev_b32_e32 v106, 16, v103
	v_and_b32_e32 v107, s59, v103
	s_nop 7
	s_nop 3
	ds_write_b32 v187, v72
	ds_write_b32 v187, v73 offset:80
	ds_write_b32 v187, v74 offset:160
	ds_write_b32 v187, v75 offset:240
	ds_read_b128 v[76:79], v188
	s_waitcnt lgkmcnt(0)
	v_add_f32_e32 v108, v76, v104
	v_add_f32_e32 v109, v77, v105
	v_add_f32_e32 v110, v78, v106
	v_add_f32_e32 v111, v79, v107
	v_bfe_u32 v112, v108, 16, 1
	v_bfe_u32 v113, v109, 16, 1
	v_bfe_u32 v114, v110, 16, 1
	v_bfe_u32 v115, v111, 16, 1
	v_add3_u32 v108, v108, v112, s27
	v_add3_u32 v109, v109, v113, s27
	v_add3_u32 v110, v110, v114, s27
	v_add3_u32 v111, v111, v115, s27
	v_lshrrev_b32_e32 v116, 16, v108
	v_lshrrev_b32_e32 v117, 16, v110
	v_and_or_b32 v118, v109, s59, v116
	v_and_or_b32 v119, v111, s59, v117
	s_add_u32 s48, s4, 0x18000
	s_addc_u32 s49, s5, 0
	global_store_dwordx2 v186, v[118:119], s[48:49]
	s_add_u32 s60, s54, 0x630000
	s_addc_u32 s61, s55, 0
	s_add_i32 m0, s58, 0x1000
	s_nop 0
	global_load_lds_dwordx4 v178, s[60:61]
	s_add_i32 m0, s58, 0x1400
	s_nop 0
	global_load_lds_dwordx4 v179, s[60:61]
	s_add_i32 m0, s58, 0x1800
	s_nop 0
	global_load_lds_dwordx4 v180, s[60:61]
	s_add_i32 m0, s58, 0x1c00
	s_nop 0
	global_load_lds_dwordx4 v181, s[60:61]
	s_add_u32 s16, s4, 0x108000
	s_addc_u32 s17, s5, 0
	global_load_dwordx2 v[102:103], v186, s[16:17]
	ds_read_b128 v[40:43], v38 offset:34816
	ds_read_b128 v[44:47], v38 offset:34880
	ds_read_b128 v[48:51], v38 offset:34944
	ds_read_b128 v[52:55], v38 offset:35008
	s_waitcnt vmcnt(6)
	ds_read_b128 v[56:59], v182
	ds_read_b128 v[60:63], v183
	ds_read_b128 v[64:67], v184
	ds_read_b128 v[68:71], v185
	s_waitcnt lgkmcnt(0)
	v_mfma_f32_16x16x32_bf16 v[72:75], v[56:59], v[40:43], 0
	v_mfma_f32_16x16x32_bf16 v[72:75], v[60:63], v[44:47], v[72:75]
	v_mfma_f32_16x16x32_bf16 v[72:75], v[64:67], v[48:51], v[72:75]
	v_mfma_f32_16x16x32_bf16 v[72:75], v[68:71], v[52:55], v[72:75]
	v_lshlrev_b32_e32 v104, 16, v100
	v_and_b32_e32 v105, s59, v100
	v_lshlrev_b32_e32 v106, 16, v101
	v_and_b32_e32 v107, s59, v101
	s_nop 7
	s_nop 3
	ds_write_b32 v187, v72
	ds_write_b32 v187, v73 offset:80
	ds_write_b32 v187, v74 offset:160
	ds_write_b32 v187, v75 offset:240
	ds_read_b128 v[76:79], v188
	s_waitcnt lgkmcnt(0)
	v_add_f32_e32 v108, v76, v104
	v_add_f32_e32 v109, v77, v105
	v_add_f32_e32 v110, v78, v106
	v_add_f32_e32 v111, v79, v107
	v_bfe_u32 v112, v108, 16, 1
	v_bfe_u32 v113, v109, 16, 1
	v_bfe_u32 v114, v110, 16, 1
	v_bfe_u32 v115, v111, 16, 1
	v_add3_u32 v108, v108, v112, s27
	v_add3_u32 v109, v109, v113, s27
	v_add3_u32 v110, v110, v114, s27
	v_add3_u32 v111, v111, v115, s27
	v_lshrrev_b32_e32 v116, 16, v108
	v_lshrrev_b32_e32 v117, 16, v110
	v_and_or_b32 v118, v109, s59, v116
	v_and_or_b32 v119, v111, s59, v117
	s_add_u32 s48, s4, 0x100000
	s_addc_u32 s49, s5, 0
	global_store_dwordx2 v186, v[118:119], s[48:49]
	s_add_u32 s60, s54, 0x660000
	s_addc_u32 s61, s55, 0
	s_add_i32 m0, s58, 0x0
	s_nop 0
	global_load_lds_dwordx4 v178, s[60:61]
	s_add_i32 m0, s58, 0x400
	s_nop 0
	global_load_lds_dwordx4 v179, s[60:61]
	s_add_i32 m0, s58, 0x800
	s_nop 0
	global_load_lds_dwordx4 v180, s[60:61]
	s_add_i32 m0, s58, 0xc00
	s_nop 0
	global_load_lds_dwordx4 v181, s[60:61]
	s_add_u32 s16, s4, 0x110000
	s_addc_u32 s17, s5, 0
	global_load_dwordx2 v[100:101], v186, s[16:17]
	s_waitcnt vmcnt(6)
; #define LAS __attribute__((address_space(3)))
; __device__ __forceinline__ unsigned f2bf(float f) { unsigned u = __float_as_uint(f); return (u + 0x7fffu + ((u >> 16) & 1u)) >> 16; }
; __device__ __forceinline__ float bf2f(unsigned h) { return __uint_as_float(h << 16); }
; #define MFMA16(a, b, c) __builtin_amdgcn_mfma_f32_16x16x32_bf16((a), (b), (c), 0, 0, 0)
; __device__ __forceinline__ void hg_b_item(const Params& p, LAS unsigned char* lds, int item, bool dry = false) {
;     ...
;         for (int c2 = 0; c2 < 2; ++c2) { const int g = wave + 8 * c2, nB = 16 * G16 + g; const size_t roB = (size_t)nB * 64 * ZW;
;             bf16x8 bS[4];
; #pragma unroll
;             for (int k = 0; k < 4; ++k) bS[k] = *(const LAS bf16x8*)(SB + g * 2176 + fr * 136 + 32 * k + 8 * fq);
; #pragma unroll
;             for (int lt = 0; lt < 4; ++lt) { f32x4 acc = (f32x4){0.f, 0.f, 0.f, 0.f}; unsigned short oO[4];
; #pragma unroll
;                 for (int r = 0; r < 4; ++r) oO[r] = pO[(size_t)(nB * 64 + 16 * lt + r) * D];
; #pragma unroll
;                 for (int k = 0; k < 4; ++k) { const bf16x8 a = *(const bf16x8*)(pQ + roB + (size_t)(16 * lt) * ZW + 32 * k); acc = MFMA16(a, bS[k], acc); }
; #pragma unroll
;                 for (int r = 0; r < 4; ++r) { const float nv = bf2f(oO[r]) + acc[r]; if (!dry) pO[(size_t)(nB * 64 + 16 * lt + r) * D] = (bf16_t)f2bf(nv); else if (nv == 123456.0f) pO[0] = 0; } } }
;         asm volatile("s_waitcnt lgkmcnt(0)" ::: "memory"); __builtin_amdgcn_s_barrier(); asm volatile("" ::: "memory");
	ds_read_b128 v[56:59], v182 offset:4096
	ds_read_b128 v[60:63], v183 offset:4096
	ds_read_b128 v[64:67], v184 offset:4096
	ds_read_b128 v[68:71], v185 offset:4096
	s_waitcnt lgkmcnt(0)
	v_mfma_f32_16x16x32_bf16 v[72:75], v[56:59], v[40:43], 0
	v_mfma_f32_16x16x32_bf16 v[72:75], v[60:63], v[44:47], v[72:75]
	v_mfma_f32_16x16x32_bf16 v[72:75], v[64:67], v[48:51], v[72:75]
	v_mfma_f32_16x16x32_bf16 v[72:75], v[68:71], v[52:55], v[72:75]
	v_lshlrev_b32_e32 v104, 16, v102
	v_and_b32_e32 v105, s59, v102
	v_lshlrev_b32_e32 v106, 16, v103
	v_and_b32_e32 v107, s59, v103
	s_nop 7
	s_nop 3
	ds_write_b32 v187, v72
	ds_write_b32 v187, v73 offset:80
	ds_write_b32 v187, v74 offset:160
	ds_write_b32 v187, v75 offset:240
	ds_read_b128 v[76:79], v188
	s_waitcnt lgkmcnt(0)
	v_add_f32_e32 v108, v76, v104
	v_add_f32_e32 v109, v77, v105
	v_add_f32_e32 v110, v78, v106
	v_add_f32_e32 v111, v79, v107
	v_bfe_u32 v112, v108, 16, 1
	v_bfe_u32 v113, v109, 16, 1
	v_bfe_u32 v114, v110, 16, 1
	v_bfe_u32 v115, v111, 16, 1
	v_add3_u32 v108, v108, v112, s27
	v_add3_u32 v109, v109, v113, s27
	v_add3_u32 v110, v110, v114, s27
	v_add3_u32 v111, v111, v115, s27
	v_lshrrev_b32_e32 v116, 16, v108
	v_lshrrev_b32_e32 v117, 16, v110
	v_and_or_b32 v118, v109, s59, v116
	v_and_or_b32 v119, v111, s59, v117
	s_add_u32 s48, s4, 0x108000
	s_addc_u32 s49, s5, 0
	global_store_dwordx2 v186, v[118:119], s[48:49]
	s_add_u32 s60, s54, 0x690000
	s_addc_u32 s61, s55, 0
	s_add_i32 m0, s58, 0x1000
	s_nop 0
	global_load_lds_dwordx4 v178, s[60:61]
	s_add_i32 m0, s58, 0x1400
	s_nop 0
	global_load_lds_dwordx4 v179, s[60:61]
	s_add_i32 m0, s58, 0x1800
	s_nop 0
	global_load_lds_dwordx4 v180, s[60:61]
	s_add_i32 m0, s58, 0x1c00
	s_nop 0
	global_load_lds_dwordx4 v181, s[60:61]
	s_add_u32 s16, s4, 0x118000
	s_addc_u32 s17, s5, 0
	global_load_dwordx2 v[102:103], v186, s[16:17]
	s_waitcnt vmcnt(6)
	ds_read_b128 v[56:59], v182
	ds_read_b128 v[60:63], v183
	ds_read_b128 v[64:67], v184
	ds_read_b128 v[68:71], v185
	s_waitcnt lgkmcnt(0)
	v_mfma_f32_16x16x32_bf16 v[72:75], v[56:59], v[40:43], 0
	v_mfma_f32_16x16x32_bf16 v[72:75], v[60:63], v[44:47], v[72:75]
	v_mfma_f32_16x16x32_bf16 v[72:75], v[64:67], v[48:51], v[72:75]
	v_mfma_f32_16x16x32_bf16 v[72:75], v[68:71], v[52:55], v[72:75]
	v_lshlrev_b32_e32 v104, 16, v100
	v_and_b32_e32 v105, s59, v100
	v_lshlrev_b32_e32 v106, 16, v101
	v_and_b32_e32 v107, s59, v101
	s_nop 7
	s_nop 3
	ds_write_b32 v187, v72
	ds_write_b32 v187, v73 offset:80
	ds_write_b32 v187, v74 offset:160
	ds_write_b32 v187, v75 offset:240
	ds_read_b128 v[76:79], v188
	s_waitcnt lgkmcnt(0)
	v_add_f32_e32 v108, v76, v104
	v_add_f32_e32 v109, v77, v105
	v_add_f32_e32 v110, v78, v106
	v_add_f32_e32 v111, v79, v107
	v_bfe_u32 v112, v108, 16, 1
	v_bfe_u32 v113, v109, 16, 1
	v_bfe_u32 v114, v110, 16, 1
	v_bfe_u32 v115, v111, 16, 1
	v_add3_u32 v108, v108, v112, s27
	v_add3_u32 v109, v109, v113, s27
	v_add3_u32 v110, v110, v114, s27
	v_add3_u32 v111, v111, v115, s27
	v_lshrrev_b32_e32 v116, 16, v108
	v_lshrrev_b32_e32 v117, 16, v110
	v_and_or_b32 v118, v109, s59, v116
	v_and_or_b32 v119, v111, s59, v117
	s_add_u32 s48, s4, 0x110000
	s_addc_u32 s49, s5, 0
	global_store_dwordx2 v186, v[118:119], s[48:49]
	s_waitcnt vmcnt(1)
	ds_read_b128 v[56:59], v182 offset:4096
	ds_read_b128 v[60:63], v183 offset:4096
	ds_read_b128 v[64:67], v184 offset:4096
	ds_read_b128 v[68:71], v185 offset:4096
	s_waitcnt lgkmcnt(0)
	v_mfma_f32_16x16x32_bf16 v[72:75], v[56:59], v[40:43], 0
	v_mfma_f32_16x16x32_bf16 v[72:75], v[60:63], v[44:47], v[72:75]
	v_mfma_f32_16x16x32_bf16 v[72:75], v[64:67], v[48:51], v[72:75]
	v_mfma_f32_16x16x32_bf16 v[72:75], v[68:71], v[52:55], v[72:75]
	v_lshlrev_b32_e32 v104, 16, v102
	v_and_b32_e32 v105, s59, v102
	v_lshlrev_b32_e32 v106, 16, v103
	v_and_b32_e32 v107, s59, v103
	s_nop 7
	s_nop 3
	ds_write_b32 v187, v72
	ds_write_b32 v187, v73 offset:80
	ds_write_b32 v187, v74 offset:160
	ds_write_b32 v187, v75 offset:240
	ds_read_b128 v[76:79], v188
	s_waitcnt lgkmcnt(0)
	v_add_f32_e32 v108, v76, v104
	v_add_f32_e32 v109, v77, v105
	v_add_f32_e32 v110, v78, v106
	v_add_f32_e32 v111, v79, v107
	v_bfe_u32 v112, v108, 16, 1
	v_bfe_u32 v113, v109, 16, 1
	v_bfe_u32 v114, v110, 16, 1
	v_bfe_u32 v115, v111, 16, 1
	v_add3_u32 v108, v108, v112, s27
	v_add3_u32 v109, v109, v113, s27
	v_add3_u32 v110, v110, v114, s27
	v_add3_u32 v111, v111, v115, s27
	v_lshrrev_b32_e32 v116, 16, v108
	v_lshrrev_b32_e32 v117, 16, v110
	v_and_or_b32 v118, v109, s59, v116
	v_and_or_b32 v119, v111, s59, v117
	s_add_u32 s48, s4, 0x118000
	s_addc_u32 s49, s5, 0
	global_store_dwordx2 v186, v[118:119], s[48:49]
	s_barrier
	ds_write_b128 v171, v[80:83]
	ds_write_b128 v171, v[84:87] offset:17408
	ds_write_b128 v171, v[88:91] offset:34816
	ds_write_b128 v171, v[92:95] offset:52224
	s_cmp_eq_u32 s8, 4
	s_waitcnt lgkmcnt(0)
	s_barrier
	s_cbranch_scc0 .LBB0_203
	s_add_i32 s50, s50, s52
	s_cmpk_gt_i32 s50, 0xff
	s_cbranch_scc0 .LBB0_202
